# loop-edge trimming: branch-free next-tile pop at the three flash loop heads (two taken branches fewer per iteration)
# speedup vs baseline: 1.0028x; 1.0028x over previous
; template <int KW, int VD, bool SEL> ...
;     ...
;     int j = __ffsll((long long)tiles) - 1; tiles &= tiles - 1;
;     FL_ISSUE(0, j);
;     asm volatile("s_waitcnt vmcnt(0)" ::: "memory");
;     __syncthreads();
;     int cur = 0;
;     const int kswz = (KW == 64) ? ((fr >> 1) & 7) : fr;
;     const int vswz = (fr >> 1) & 7;
;     while (true) {
;         int jn = -1;
;         if (tiles) { jn = __ffsll((long long)tiles) - 1; tiles &= tiles - 1; FL_ISSUE(cur ^ 1, jn); }
;         const char* sK = smem + cur * BUFB;
;         const char* sV = smem + cur * BUFB + KB;
;         f32x4 s[2][4];
;         const float mref0 = (mrow[0] < -1e29f) ? 0.f : mrow[0], mref1 = (mrow[1] < -1e29f) ? 0.f : mrow[1];
;         const float ci0 = (SEL && !((((const u64*)(smem + 69632))[fr] >> j) & 1ull)) ? -1e30f : -mref0;
;         const float ci1 = (SEL && !((((const u64*)(smem + 69632))[16 + fr] >> j) & 1ull)) ? -1e30f : -mref1;
.LBB0_370:
.LBB0_371:
	s_add_u32 s0, s2, -1
	s_addc_u32 s1, s3, -1
	s_lshl_b32 s12, s10, 14
	s_ff1_i32_b64 s11, s[2:3]
	s_and_b64 s[2:3], s[0:1], s[2:3]
.LBB0_372:
.LBB0_373:
	v_add_u32_e32 v72, s12, v129
	ds_read2_b64 v[52:55], v124 offset1:16
	v_add_u32_e32 v141, v72, v125
	ds_read_b128 v[56:59], v141
	s_cmp_lt_i32 s11, 0
	s_cbranch_scc1 .Lfh_sel_nodma
	v_readfirstlane_b32 s13, v123
	s_mul_i32 s14, s11, 0x44000
	s_add_u32 s14, s6, s14
	s_addc_u32 s15, s7, 0
	s_add_u32 s14, s14, 0xc00
	s_addc_u32 s15, s15, 0
	s_lshl_b32 s5, s11, 7
	s_add_u32 s22, s8, s5
	s_addc_u32 s23, s9, 0
	s_xor_b32 s5, s12, 0x4000
	s_add_i32 s5, s5, s13
	s_mov_b32 m0, s5
	s_nop 0
	global_load_lds_dwordx4 v246, s[14:15]
	s_add_i32 m0, s5, 0x1000
	s_nop 0
	global_load_lds_dwordx4 v247, s[14:15]
	s_add_i32 m0, s5, 0x2000
	s_nop 0
	global_load_lds_dwordx4 v248, s[22:23]
	s_add_i32 m0, s5, 0x3000
	s_nop 0
	global_load_lds_dwordx4 v249, s[22:23]

; template <int KW, int VD, bool SEL> ...
;     ...
;     int j = __ffsll((long long)tiles) - 1; tiles &= tiles - 1;
;     FL_ISSUE(0, j);
;     asm volatile("s_waitcnt vmcnt(0)" ::: "memory");
;     __syncthreads();
;     int cur = 0;
;     const int kswz = (KW == 64) ? ((fr >> 1) & 7) : fr;
;     const int vswz = (fr >> 1) & 7;
;     while (true) {
;         int jn = -1;
;         if (tiles) { jn = __ffsll((long long)tiles) - 1; tiles &= tiles - 1; FL_ISSUE(cur ^ 1, jn); }
;         const char* sK = smem + cur * BUFB;
;         const char* sV = smem + cur * BUFB + KB;
;         f32x4 s[2][4];
;         const float mref0 = (mrow[0] < -1e29f) ? 0.f : mrow[0], mref1 = (mrow[1] < -1e29f) ? 0.f : mrow[1];
;         const float ci0 = (SEL && !((((const u64*)(smem + 69632))[fr] >> j) & 1ull)) ? -1e30f : -mref0;
;         const float ci1 = (SEL && !((((const u64*)(smem + 69632))[16 + fr] >> j) & 1ull)) ? -1e30f : -mref1;
;         const f32x4 cinit0 = (f32x4){ci0, ci0, ci0, ci0}, cinit1 = (f32x4){ci1, ci1, ci1, ci1};
; #pragma unroll
;         for (int tt = 0; tt < 4; ++tt) {
;             const int kr = 32 * (tt >> 1) + (fr >> 2) * 8 + (tt & 1) * 4 + (fr & 3);
;             const bf16x8 kf0 = *(const bf16x8*)(sK + kr * KROWB + (((kcol >> 3) + fq) ^ kswz) * 16);
;             const bf16x8 kf1 = *(const bf16x8*)(sK + kr * KROWB + (((kcol >> 3) + 4 + fq) ^ kswz) * 16);
.LBB0_391:
.LBB0_392:
	s_add_u32 s0, s2, -1
	s_addc_u32 s1, s3, -1
	s_lshl_b32 s13, s11, 14
	s_ff1_i32_b64 s12, s[2:3]
	s_mov_b32 s16, 0xefa18f08
	s_and_b64 s[2:3], s[0:1], s[2:3]
.LBB0_393:
.LBB0_394:
	v_add_u32_e32 v3, s13, v127
	v_add_u32_e32 v129, v3, v123
	ds_read_b128 v[52:55], v129
	ds_read_b128 v[60:63], v129 offset:512
	v_cmp_ngt_f32_e32 vcc, s16, v0
	v_add_u32_e32 v3, v3, v124
	ds_read_b128 v[68:71], v3
	ds_read_b128 v[72:75], v3 offset:512
	s_cmp_lt_i32 s12, 0
	s_cbranch_scc1 .Lfh_win_nodma
	v_readfirstlane_b32 s0, v106
	s_mul_i32 s14, s12, 0x44000
	s_add_u32 s14, s6, s14
	s_addc_u32 s15, s7, 0
	s_add_u32 s14, s14, 0xe00
	s_addc_u32 s15, s15, 0
	s_lshl_b32 s5, s12, 7
	s_add_u32 s22, s8, s5
	s_addc_u32 s23, s9, 0
	s_xor_b32 s5, s13, 0x4000
	s_add_i32 s5, s5, s0
	s_mov_b32 m0, s5
	s_nop 0
	global_load_lds_dwordx4 v250, s[14:15]
	s_add_i32 m0, s5, 0x1000
	s_nop 0
	global_load_lds_dwordx4 v251, s[14:15]
	s_add_i32 m0, s5, 0x2000
	s_nop 0
	global_load_lds_dwordx4 v252, s[22:23]
	s_add_i32 m0, s5, 0x3000
	s_nop 0
	global_load_lds_dwordx4 v253, s[22:23]

; template <int KW, int VD, bool SEL> ...
;     ...
;     int j = __ffsll((long long)tiles) - 1; tiles &= tiles - 1;
;     FL_ISSUE(0, j);
;     asm volatile("s_waitcnt vmcnt(0)" ::: "memory");
;     __syncthreads();
;     int cur = 0;
;     const int kswz = (KW == 64) ? ((fr >> 1) & 7) : fr;
;     const int vswz = (fr >> 1) & 7;
;     while (true) {
;         int jn = -1;
;         if (tiles) { jn = __ffsll((long long)tiles) - 1; tiles &= tiles - 1; FL_ISSUE(cur ^ 1, jn); }
;         const char* sK = smem + cur * BUFB;
;         const char* sV = smem + cur * BUFB + KB;
;         f32x4 s[2][4];
;         const float mref0 = (mrow[0] < -1e29f) ? 0.f : mrow[0], mref1 = (mrow[1] < -1e29f) ? 0.f : mrow[1];
;         const float ci0 = (SEL && !((((const u64*)(smem + 69632))[fr] >> j) & 1ull)) ? -1e30f : -mref0;
;         const float ci1 = (SEL && !((((const u64*)(smem + 69632))[16 + fr] >> j) & 1ull)) ? -1e30f : -mref1;
;         const f32x4 cinit0 = (f32x4){ci0, ci0, ci0, ci0}, cinit1 = (f32x4){ci1, ci1, ci1, ci1};
; #pragma unroll
;         for (int tt = 0; tt < 4; ++tt) {
;             const int kr = 32 * (tt >> 1) + (fr >> 2) * 8 + (tt & 1) * 4 + (fr & 3);
;             const bf16x8 kf0 = *(const bf16x8*)(sK + kr * KROWB + (((kcol >> 3) + fq) ^ kswz) * 16);
;             const bf16x8 kf1 = *(const bf16x8*)(sK + kr * KROWB + (((kcol >> 3) + 4 + fq) ^ kswz) * 16);
.LBB0_821:
.LBB0_822:
	s_add_u32 s8, s6, -1
	s_addc_u32 s9, s7, -1
	s_lshl_b32 s26, s24, 15
	s_ff1_i32_b64 s25, s[6:7]
	s_and_b64 s[6:7], s[8:9], s[6:7]
.LBB0_823:
.LBB0_824:
	v_add_u32_e32 v100, s26, v179
	v_add_u32_e32 v185, v100, v175
	ds_read_b128 v[80:83], v185
	ds_read_b128 v[92:95], v185 offset:1024
	v_cmp_ngt_f32_e32 vcc, s13, v182
	v_add_u32_e32 v194, v100, v176
	ds_read_b128 v[100:103], v194
	ds_read_b128 v[186:189], v194 offset:1024
	s_cmp_lt_i32 s25, 0
	s_cbranch_scc1 .Lfh_diff_nodma
	v_readfirstlane_b32 s27, v174
	s_mul_i32 s28, s25, 0x44000
	s_add_u32 s28, s20, s28
	s_addc_u32 s29, s21, 0
	s_add_u32 s28, s28, s0
	s_addc_u32 s29, s29, s1
	s_lshl_b32 s11, s25, 7
	s_add_u32 s8, s22, s11
	s_addc_u32 s9, s23, 0
	s_xor_b32 s11, s26, 0x8000
	s_add_i32 s11, s11, s27
	s_mov_b32 m0, s11
	s_nop 0
	global_load_lds_dwordx4 v246, s[28:29]
	s_add_i32 m0, s11, 0x1000
	s_nop 0
	global_load_lds_dwordx4 v247, s[28:29]
	s_add_i32 m0, s11, 0x2000
	s_nop 0
	global_load_lds_dwordx4 v248, s[28:29]
	s_add_i32 m0, s11, 0x3000
	s_nop 0
	global_load_lds_dwordx4 v249, s[28:29]
	s_add_i32 m0, s11, 0x4000
	s_nop 0
	global_load_lds_dwordx4 v250, s[8:9]
	s_add_i32 m0, s11, 0x5000
	s_nop 0
	global_load_lds_dwordx4 v251, s[8:9]
	s_add_i32 m0, s11, 0x6000
	s_nop 0
	global_load_lds_dwordx4 v252, s[8:9]
	s_add_i32 m0, s11, 0x7000
	s_nop 0
	global_load_lds_dwordx4 v253, s[8:9]
